# mixer-D loop: packed f32 ops split into scalar ops, pair-packing moves removed by copy propagation (slots kept as s_nop)
# baseline (speedup 1.0000x reference)
.LBB0_500:
	s_sub_i32 s0, s82, 63
	s_cmp_ge_i32 s0, s14
	s_cbranch_scc1 .LBB0_506
	s_mul_i32 s12, s2, 0x9000
	v_add3_u32 v12, s12, v209, v212
	ds_read_b128 v[0:3], v12
	ds_read_b128 v[4:7], v12 offset:32
	s_cmp_ge_i32 s82, s83
	s_mov_b64 s[0:1], -1
	s_waitcnt lgkmcnt(1)
	v_mfma_f32_32x32x16_bf16 v[64:79], v[0:3], v[96:99], 0
	ds_read_b128 v[0:3], v12 offset:4608
	ds_read_b128 v[8:11], v12 offset:4640
	s_waitcnt lgkmcnt(2)
	v_mfma_f32_32x32x16_bf16 v[64:79], v[4:7], v[100:103], v[64:79]
	s_waitcnt lgkmcnt(1)
	v_mfma_f32_32x32x16_bf16 v[80:95], v[0:3], v[96:99], 0
	ds_read_b128 v[0:3], v12 offset:64
	ds_read_b128 v[4:7], v12 offset:96
	s_waitcnt lgkmcnt(1)
	v_mfma_f32_32x32x16_bf16 v[64:79], v[0:3], v[104:107], v[64:79]
	ds_read_b128 v[0:3], v12 offset:4672
	v_mfma_f32_32x32x16_bf16 v[80:95], v[8:11], v[100:103], v[80:95]
	s_waitcnt lgkmcnt(1)
	v_mfma_f32_32x32x16_bf16 v[64:79], v[4:7], v[108:111], v[64:79]
	ds_read_b128 v[4:7], v12 offset:4704
	s_waitcnt lgkmcnt(1)
	v_mfma_f32_32x32x16_bf16 v[80:95], v[0:3], v[104:107], v[80:95]
	s_nop 8
	v_mul_f32_e32 v142, 0x3e38aa3b, v67
	v_mul_f32_e32 v148, 0x3e38aa3b, v68
	v_mul_f32_e32 v146, 0x3e38aa3b, v69
	v_mul_f32_e32 v144, 0x3e38aa3b, v71
	v_mul_f32_e32 v72, 0x3e38aa3b, v72
	v_mul_f32_e32 v152, 0x3e38aa3b, v73
	v_mul_f32_e32 v150, 0x3e38aa3b, v75
	s_waitcnt lgkmcnt(0)
	v_mfma_f32_32x32x16_bf16 v[80:95], v[4:7], v[108:111], v[80:95]
	v_mul_f32_e32 v154, 0x3e38aa3b, v79
	s_nop 10
	v_mul_f32_e32 v156, 0x3e38aa3b, v80
	v_mul_f32_e32 v158, 0x3e38aa3b, v81
	v_mul_f32_e32 v84, 0x3e38aa3b, v84
	v_mul_f32_e32 v160, 0x3e38aa3b, v85
	v_mul_f32_e32 v164, 0x3e38aa3b, v90
	v_mul_f32_e32 v162, 0x3e38aa3b, v91
	v_mul_f32_e32 v166, 0x3e38aa3b, v92
	v_mul_f32_e32 v192, 0x3e38aa3b, v94
	s_cbranch_scc0 .LBB0_503
	v_mul_f32_e32 v0, 0x3e38aa3b, v64
	v_exp_f32_e64 v1, -|v0|
	v_mul_f32_e32 v2, 0x3e38aa3b, v65
	v_exp_f32_e64 v3, -|v2|
	v_mul_f32_e32 v170, 0x3e38aa3b, v66
	v_add_f32_e32 v1, 1.0, v1
	v_log_f32_e32 v1, v1
	v_min_f32_e64 v4, -v0, 0
	v_add_f32_e32 v3, 1.0, v3
	v_log_f32_e32 v3, v3
	v_sub_f32_e32 v1, v4, v1
	v_exp_f32_e64 v4, -|v170|
	v_cmp_lt_i32_e32 vcc, 0, v214
	v_cmp_lt_i32_e64 s[0:1], 1, v214
	v_writelane_b32 v254, s12, 50
	v_cndmask_b32_e32 v168, 0, v1, vcc
	v_min_f32_e64 v1, -v2, 0
	v_sub_f32_e32 v1, v1, v3
	v_add_f32_e32 v3, 1.0, v4
	v_log_f32_e32 v3, v3
	v_exp_f32_e64 v4, -|v142|
	v_cndmask_b32_e64 v172, 0, v1, s[0:1]
	v_min_f32_e64 v1, -v170, 0
	v_sub_f32_e32 v1, v1, v3
	v_add_f32_e32 v3, 1.0, v4
	v_log_f32_e32 v3, v3
	v_exp_f32_e64 v4, -|v148|
	v_cmp_lt_i32_e64 s[12:13], 2, v214
	v_cmp_lt_i32_e64 s[14:15], 3, v214
	v_mul_f32_e32 v5, 0x3e38aa3b, v70
	v_cndmask_b32_e64 v174, 0, v1, s[12:13]
	v_min_f32_e64 v1, -v142, 0
	v_sub_f32_e32 v1, v1, v3
	v_add_f32_e32 v3, 1.0, v4
	v_log_f32_e32 v3, v3
	v_exp_f32_e64 v4, -|v146|
	v_cndmask_b32_e64 v176, 0, v1, s[14:15]
	v_min_f32_e64 v1, -v148, 0
	v_sub_f32_e32 v1, v1, v3
	v_add_f32_e32 v3, 1.0, v4
	v_log_f32_e32 v3, v3
	v_exp_f32_e64 v6, -|v5|
	v_cmp_lt_i32_e64 s[16:17], 8, v214
	v_exp_f32_e64 v7, -|v144|
	v_writelane_b32 v254, s3, 51
	v_cndmask_b32_e64 v4, 0, v1, s[16:17]
	v_min_f32_e64 v1, -v146, 0
	v_sub_f32_e32 v1, v1, v3
	v_add_f32_e32 v3, 1.0, v6
	v_log_f32_e32 v3, v3
	s_mov_b32 s33, s2
	s_mov_b64 s[2:3], s[18:19]
	v_cmp_lt_i32_e64 s[18:19], 9, v214
	v_cmp_lt_i32_e64 s[22:23], 10, v214
	v_exp_f32_e64 v8, -|v152|
	v_cndmask_b32_e64 v6, 0, v1, s[18:19]
	v_min_f32_e64 v1, -v5, 0
	v_sub_f32_e32 v1, v1, v3
	v_add_f32_e32 v3, 1.0, v7
	v_log_f32_e32 v3, v3
	v_exp_f32_e64 v7, -|v72|
	v_cndmask_b32_e64 v5, 0, v1, s[22:23]
	v_min_f32_e64 v1, -v144, 0
	v_sub_f32_e32 v1, v1, v3
	v_add_f32_e32 v3, 1.0, v7
	v_log_f32_e32 v3, v3
	v_cmp_lt_i32_e64 s[24:25], 11, v214
	v_mul_f32_e32 v178, 0x3e38aa3b, v74
	v_exp_f32_e64 v9, -|v178|
	v_cndmask_b32_e64 v7, 0, v1, s[24:25]
	v_min_f32_e64 v1, -v72, 0
	v_sub_f32_e32 v1, v1, v3
	v_add_f32_e32 v3, 1.0, v8
	v_log_f32_e32 v3, v3
	v_cmp_lt_i32_e64 s[26:27], 16, v214
	v_cmp_lt_i32_e64 s[28:29], 17, v214
	v_mul_f32_e32 v12, 0x3e38aa3b, v76
	v_cndmask_b32_e64 v8, 0, v1, s[26:27]
	v_min_f32_e64 v1, -v152, 0
	v_sub_f32_e32 v1, v1, v3
	v_add_f32_e32 v3, 1.0, v9
	v_log_f32_e32 v3, v3
	v_exp_f32_e64 v9, -|v150|
	v_cndmask_b32_e64 v10, 0, v1, s[28:29]
	v_min_f32_e64 v1, -v178, 0
	v_sub_f32_e32 v1, v1, v3
	v_add_f32_e32 v3, 1.0, v9
	v_log_f32_e32 v3, v3
	v_exp_f32_e64 v11, -|v12|
	v_cmp_lt_i32_e64 s[30:31], 18, v214
	v_mul_f32_e32 v14, 0x3e38aa3b, v77
	v_exp_f32_e64 v13, -|v14|
	v_cndmask_b32_e64 v9, 0, v1, s[30:31]
	v_min_f32_e64 v1, -v150, 0
	v_sub_f32_e32 v1, v1, v3
	v_add_f32_e32 v3, 1.0, v11
	v_log_f32_e32 v3, v3
	v_cmp_lt_i32_e64 s[34:35], 19, v214
	v_mul_f32_e32 v184, 0x3e38aa3b, v78
	v_cmp_lt_i32_e64 s[36:37], 24, v214
	v_cndmask_b32_e64 v11, 0, v1, s[34:35]
	v_min_f32_e64 v1, -v12, 0
	v_sub_f32_e32 v1, v1, v3
	v_add_f32_e32 v3, 1.0, v13
	v_log_f32_e32 v3, v3
	v_exp_f32_e64 v13, -|v184|
	v_cndmask_b32_e64 v180, 0, v1, s[36:37]
	v_min_f32_e64 v1, -v14, 0
	v_sub_f32_e32 v1, v1, v3
	v_add_f32_e32 v3, 1.0, v13
	v_log_f32_e32 v3, v3
	v_exp_f32_e64 v13, -|v154|
	v_cmp_lt_i32_e64 s[38:39], 25, v214
	v_cmp_lt_i32_e64 s[40:41], 26, v214
	v_cmp_lt_i32_e64 s[42:43], 27, v214
	v_cndmask_b32_e64 v182, 0, v1, s[38:39]
	v_min_f32_e64 v1, -v184, 0
	v_sub_f32_e32 v1, v1, v3
	v_add_f32_e32 v3, 1.0, v13
	v_log_f32_e32 v3, v3
	v_exp_f32_e64 v13, -|v156|
	v_cndmask_b32_e64 v186, 0, v1, s[40:41]
	v_min_f32_e64 v1, -v154, 0
	v_sub_f32_e32 v1, v1, v3
	v_add_f32_e32 v3, 1.0, v13
	v_log_f32_e32 v3, v3
	v_exp_f32_e64 v13, -|v158|
	v_cndmask_b32_e64 v188, 0, v1, s[42:43]
	v_min_f32_e64 v1, -v156, 0
	v_sub_f32_e32 v1, v1, v3
	v_add_f32_e32 v3, 1.0, v13
	v_mul_f32_e32 v13, 0x3e38aa3b, v82
	v_log_f32_e32 v3, v3
	v_exp_f32_e64 v15, -|v13|
	v_cmp_lt_i32_e64 s[44:45], 32, v214
	v_cmp_lt_i32_e64 s[46:47], 33, v214
	v_cmp_lt_i32_e64 s[48:49], 34, v214
	v_cndmask_b32_e64 v16, 0, v1, s[44:45]
	v_min_f32_e64 v1, -v158, 0
	v_sub_f32_e32 v1, v1, v3
	v_add_f32_e32 v3, 1.0, v15
	v_mul_f32_e32 v15, 0x3e38aa3b, v83
	v_log_f32_e32 v3, v3
	v_exp_f32_e64 v17, -|v15|
	v_cndmask_b32_e64 v18, 0, v1, s[46:47]
	v_min_f32_e64 v1, -v13, 0
	v_sub_f32_e32 v1, v1, v3
	v_add_f32_e32 v3, 1.0, v17
	v_log_f32_e32 v3, v3
	v_exp_f32_e64 v13, -|v84|
	v_cndmask_b32_e64 v17, 0, v1, s[48:49]
	v_min_f32_e64 v1, -v15, 0
	v_sub_f32_e32 v1, v1, v3
	v_add_f32_e32 v3, 1.0, v13
	v_log_f32_e32 v3, v3
	v_exp_f32_e64 v13, -|v160|
	v_cmp_lt_i32_e64 s[50:51], 35, v214
	v_mul_f32_e32 v200, 0x3e38aa3b, v86
	v_cmp_lt_i32_e64 s[52:53], 40, v214
	v_cndmask_b32_e64 v19, 0, v1, s[50:51]
	v_min_f32_e64 v1, -v84, 0
	v_sub_f32_e32 v1, v1, v3
	v_add_f32_e32 v3, 1.0, v13
	v_log_f32_e32 v3, v3
	v_exp_f32_e64 v13, -|v200|
	v_cndmask_b32_e64 v20, 0, v1, s[52:53]
	v_min_f32_e64 v1, -v160, 0
	v_sub_f32_e32 v1, v1, v3
	v_add_f32_e32 v3, 1.0, v13
	v_mul_f32_e32 v216, 0x3e38aa3b, v87
	v_log_f32_e32 v3, v3
	v_exp_f32_e64 v13, -|v216|
	v_cmp_lt_i32_e64 s[54:55], 41, v214
	v_cmp_lt_i32_e64 s[56:57], 42, v214
	v_mul_f32_e32 v24, 0x3e38aa3b, v89
	v_cndmask_b32_e64 v22, 0, v1, s[54:55]
	v_min_f32_e64 v1, -v200, 0
	v_sub_f32_e32 v1, v1, v3
	v_add_f32_e32 v3, 1.0, v13
	v_mul_f32_e32 v13, 0x3e38aa3b, v88
	v_log_f32_e32 v3, v3
	v_exp_f32_e64 v15, -|v13|
	v_cndmask_b32_e64 v21, 0, v1, s[56:57]
	v_min_f32_e64 v1, -v216, 0
	v_sub_f32_e32 v1, v1, v3
	v_add_f32_e32 v3, 1.0, v15
	v_log_f32_e32 v3, v3
	v_exp_f32_e64 v15, -|v24|
	v_cmp_lt_i32_e64 s[58:59], 43, v214
	v_cmp_lt_i32_e64 s[60:61], 48, v214
	v_cmp_lt_i32_e64 s[62:63], 49, v214
	v_cndmask_b32_e64 v23, 0, v1, s[58:59]
	v_min_f32_e64 v1, -v13, 0
	v_sub_f32_e32 v1, v1, v3
	v_add_f32_e32 v3, 1.0, v15
	v_log_f32_e32 v3, v3
	v_exp_f32_e64 v13, -|v164|
	v_cndmask_b32_e64 v26, 0, v1, s[60:61]
	v_min_f32_e64 v1, -v24, 0
	v_sub_f32_e32 v1, v1, v3
	v_add_f32_e32 v3, 1.0, v13
	v_log_f32_e32 v3, v3
	v_exp_f32_e64 v13, -|v162|
	v_cndmask_b32_e64 v28, 0, v1, s[62:63]
	v_min_f32_e64 v1, -v164, 0
	v_sub_f32_e32 v1, v1, v3
	v_add_f32_e32 v3, 1.0, v13
	v_log_f32_e32 v3, v3
	v_exp_f32_e64 v13, -|v166|
	v_cmp_lt_i32_e64 s[64:65], 50, v214
	v_min_f32_e64 v25, -v166, 0
	v_and_b32_e32 v27, 64, v225
	v_cndmask_b32_e64 v29, 0, v1, s[64:65]
	v_min_f32_e64 v1, -v162, 0
	v_sub_f32_e32 v1, v1, v3
	v_add_f32_e32 v3, 1.0, v13
	v_mul_f32_e32 v13, 0x3e38aa3b, v93
	v_exp_f32_e64 v15, -|v13|
	v_log_f32_e32 v3, v3
	v_min_f32_e64 v13, -v13, 0
	v_add_f32_e32 v30, v4, v6
	v_add_f32_e32 v31, v5, v7
	v_add_f32_e32 v15, 1.0, v15
	v_sub_f32_e32 v3, v25, v3
	v_log_f32_e32 v15, v15
	v_exp_f32_e64 v25, -|v192|
	v_cmp_lt_i32_e64 s[68:69], 56, v214
	v_cmp_lt_i32_e64 s[70:71], 57, v214
	v_sub_f32_e32 v13, v13, v15
	v_add_f32_e32 v15, 1.0, v25
	v_log_f32_e32 v15, v15
	v_min_f32_e64 v25, -v192, 0
	v_add_u32_e32 v27, 64, v27
	v_add_f32_e32 v190, v30, v31
	v_add_f32_e32 v191, v31, v30
	v_sub_f32_e32 v15, v25, v15
	v_xor_b32_e32 v25, 32, v225
	v_add_f32_e32 v30, v8, v10
	v_add_f32_e32 v31, v9, v11
	v_cmp_lt_i32_e64 s[66:67], 51, v214
	v_cndmask_b32_e64 v3, 0, v3, s[68:69]
	v_cndmask_b32_e64 v13, 0, v13, s[70:71]
	v_cmp_lt_i32_e64 s[76:77], v25, v27
	v_add_f32_e32 v69, v30, v31
	v_add_f32_e32 v30, v16, v18
	v_add_f32_e32 v31, v17, v19
	v_cndmask_b32_e64 v1, 0, v1, s[66:67]
	v_cndmask_b32_e64 v25, v225, v25, s[76:77]
	v_add_f32_e32 v218, v30, v31
	v_add_f32_e32 v219, v31, v30
	v_add_f32_e32 v30, v20, v22
	v_add_f32_e32 v31, v21, v23
	v_add_f32_e32 v27, v3, v13
	v_fmac_f32_e32 v3, 0x3e38aa3b, v92
	v_mov_b32_e32 v92, v29
	s_nop 0
	s_mov_b64 s[76:77], 0x3e38aa3b
	v_lshlrev_b32_e32 v67, 2, v25
	v_add_f32_e32 v73, v30, v31
	v_add_f32_e32 v30, v29, v1
	v_add_f32_e32 v25, 0, v1
	v_fmac_f32_e32 v1, 0x3e38aa3b, v91
	v_fmac_f32_e32 v92, 0x3e38aa3b, v90
	v_mul_f32_e32 v90, s76, v95
	v_mul_f32_e32 v91, s77, v141
	v_add_f32_e32 v220, v24, v28
	v_add_f32_e32 v221, v25, v29
	v_exp_f32_e64 v31, -|v90|
	v_cmp_lt_i32_e64 s[72:73], 58, v214
	v_add_f32_e32 v228, s76, v95
	v_add_f32_e32 v229, s77, v141
	v_cmp_lt_i32_e64 s[76:77], 59, v214
	v_add_f32_e32 v29, 1.0, v31
	v_log_f32_e32 v29, v29
	v_min_f32_e64 v31, -v90, 0
	v_cndmask_b32_e64 v15, 0, v15, s[72:73]
	v_fmamk_f32 v81, v94, 0x3e38aa3b, v15
	v_sub_f32_e32 v29, v31, v29
	v_cndmask_b32_e64 v228, 0, v29, s[76:77]
	v_add_f32_e32 v29, v15, v228
	v_mov_b32_e32 v94, v26
	v_add_f32_e32 v26, v26, v28
	v_add_f32_e32 v27, v27, v29
	ds_bpermute_b32 v31, v67, v27
	v_add_f32_e32 v140, 0, v228
	v_mov_b32_e32 v91, v229
	v_add_f32_e32 v15, v15, v140
	v_fmamk_f32 v85, v93, 0x3e38aa3b, v13
	s_waitcnt lgkmcnt(0)
	v_cndmask_b32_e64 v229, 0, v31, s[8:9]
	v_add_f32_e32 v24, v28, v221
	v_add_f32_e32 v13, v13, v15
	v_add_f32_e32 v26, v26, v30
	v_add_f32_e32 v27, v27, v31
	v_add_f32_e32 v28, v90, v228
	v_add_f32_e32 v29, v91, v229
	ds_bpermute_b32 v230, v67, v26
	v_add_f32_e32 v13, v13, v29
	v_add_f32_e32 v28, v28, v29
	v_add_f32_e32 v3, v3, v13
	v_exp_f32_e32 v28, v28
	v_add_f32_e32 v15, v15, v29
	v_exp_f32_e32 v3, v3
	v_add_f32_e32 v15, v85, v15
	v_exp_f32_e32 v15, v15
	v_mov_b32_e32 v231, v193
	s_waitcnt lgkmcnt(0)
	v_add_f32_e32 v90, v26, v230
	v_add_f32_e32 v91, v27, v231
	ds_bpermute_b32 v79, v67, v73
	v_cndmask_b32_e64 v31, 0, v28, s[76:77]
	v_cndmask_b32_e64 v28, 0, v3, s[68:69]
	v_add_f32_e32 v3, v141, v91
	v_cndmask_b32_e64 v13, 0, v230, s[8:9]
	v_add_f32_e32 v3, v13, v3
	v_fmac_f32_e32 v94, 0x3e38aa3b, v88
	v_add_f32_e32 v30, v140, v29
	v_cndmask_b32_e64 v29, 0, v15, s[70:71]
	v_add_f32_e32 v1, v1, v3
	v_add_f32_e32 v13, v25, v3
	v_add_f32_e32 v15, v221, v3
	v_add_f32_e32 v3, v24, v3
	v_add_f32_e32 v3, v94, v3
	v_exp_f32_e32 v3, v3
	v_pk_add_f32 v[90:91], v[90:91], v[90:91] op_sel:[0,1] op_sel_hi:[1,0]
	v_add_f32_e32 v13, v92, v13
	v_add_f32_e32 v15, v220, v15
	v_add_f32_e32 v217, v141, v90
	s_waitcnt lgkmcnt(0)
	v_cndmask_b32_e64 v221, 0, v79, s[8:9]
	s_nop 0
	v_exp_f32_e32 v13, v13
	v_add_f32_e32 v216, v216, v23
	v_add_f32_e32 v217, v217, v221
	s_nop 0
	v_mov_b32_e32 v220, v21
	v_mov_b32_e32 v221, v23
	v_exp_f32_e32 v1, v1
	v_add_f32_e32 v200, v200, v220
	v_add_f32_e32 v201, v193, v221
	v_exp_f32_e32 v15, v15
	v_cndmask_b32_e64 v24, 0, v3, s[60:61]
	v_add_f32_e32 v3, v201, v217
	v_mov_b32_e32 v161, v201
	v_mov_b32_e32 v23, v21
	v_add_f32_e32 v3, v200, v3
	v_add_f32_e32 v200, v160, v22
	v_add_f32_e32 v201, v161, v23
	v_cndmask_b32_e64 v26, 0, v13, s[64:65]
	v_add_f32_e32 v13, v201, v217
	v_mov_b32_e32 v85, v201
	s_nop 0
	ds_bpermute_b32 v183, v67, v218
	v_cndmask_b32_e64 v27, 0, v1, s[66:67]
	v_add_f32_e32 v1, v216, v217
	v_add_f32_e32 v13, v200, v13
	v_add_f32_e32 v20, v84, v20
	v_add_f32_e32 v21, v85, v22
	v_cndmask_b32_e64 v25, 0, v15, s[62:63]
	v_exp_f32_e32 v1, v1
	v_exp_f32_e32 v13, v13
	v_add_f32_e32 v15, v21, v217
	v_add_f32_e32 v15, v20, v15
	v_exp_f32_e32 v3, v3
	v_exp_f32_e32 v15, v15
	v_add_f32_e32 v187, v73, v79
	v_mov_b32_e32 v189, v90
	v_add_f32_e32 v30, v81, v30
	v_fmac_f32_e32 v16, 0x3e38aa3b, v80
	v_add_f32_e32 v80, v186, v188
	v_add_f32_e32 v81, v187, v189
	s_nop 0
	v_cndmask_b32_e64 v23, 0, v1, s[58:59]
	v_cndmask_b32_e64 v21, 0, v13, s[54:55]
	s_waitcnt lgkmcnt(0)
	v_cndmask_b32_e64 v1, 0, v183, s[8:9]
	v_add_f32_e32 v159, 0, v19
	s_nop 0
	s_nop 0
	v_add_f32_e32 v90, v180, v182
	v_add_f32_e32 v91, v218, v183
	v_add_f32_e32 v13, v141, v81
	v_add_f32_e32 v200, v158, v18
	v_add_f32_e32 v201, v159, v17
	v_add_f32_e32 v90, v90, v80
	v_add_f32_e32 v91, v91, v81
	v_add_f32_e32 v1, v1, v13
	v_cndmask_b32_e64 v22, 0, v3, s[56:57]
	v_cndmask_b32_e64 v20, 0, v15, s[52:53]
	v_fmac_f32_e32 v19, 0x3e38aa3b, v83
	v_fmac_f32_e32 v17, 0x3e38aa3b, v82
	v_add_f32_e32 v3, v18, v201
	ds_bpermute_b32 v73, v67, v90
	v_add_f32_e32 v15, v159, v1
	v_add_f32_e32 v13, v19, v1
	v_add_f32_e32 v15, v17, v15
	v_add_f32_e32 v17, v201, v1
	v_add_f32_e32 v1, v3, v1
	v_add_f32_e32 v1, v16, v1
	v_exp_f32_e32 v1, v1
	v_exp_f32_e32 v15, v15
	v_add_f32_e32 v155, v141, v91
	s_waitcnt lgkmcnt(0)
	v_cndmask_b32_e64 v189, 0, v73, s[8:9]
	v_exp_f32_e32 v13, v13
	v_add_f32_e32 v80, v154, v188
	v_add_f32_e32 v81, v155, v189
	s_nop 0
	v_mov_b32_e32 v187, v188
	v_cndmask_b32_e64 v16, 0, v1, s[44:45]
	v_add_f32_e32 v1, v80, v81
	v_add_f32_e32 v184, v184, v186
	v_add_f32_e32 v185, v193, v187
	v_cndmask_b32_e64 v18, 0, v15, s[48:49]
	v_exp_f32_e32 v1, v1
	s_nop 0
	v_mov_b32_e32 v183, v186
	ds_bpermute_b32 v75, v67, v69
	v_add_f32_e32 v14, v14, v182
	v_add_f32_e32 v15, v185, v183
	v_cndmask_b32_e64 v19, 0, v13, s[50:51]
	v_add_f32_e32 v3, v185, v81
	v_add_f32_e32 v13, v15, v81
	v_add_f32_e32 v3, v184, v3
	v_add_f32_e32 v13, v14, v13
	v_exp_f32_e32 v3, v3
	v_exp_f32_e32 v79, v13
	v_mov_b32_e32 v13, v15
	v_mov_b32_e32 v181, v182
	v_cndmask_b32_e64 v15, 0, v1, s[42:43]
	v_add_f32_e32 v1, v90, v73
	v_add_f32_e32 v12, v12, v180
	v_add_f32_e32 v13, v13, v181
	v_add_f32_e32 v177, v1, v91
	v_add_f32_e32 v13, v13, v81
	v_add_f32_e32 v151, v141, v177
	s_waitcnt lgkmcnt(0)
	v_cndmask_b32_e64 v81, 0, v75, s[8:9]
	s_nop 0
	v_mov_b32_e32 v179, v193
	s_nop 0
	s_nop 0
	v_add_f32_e32 v80, v150, v11
	v_add_f32_e32 v81, v151, v81
	v_add_f32_e32 v90, v178, v9
	v_add_f32_e32 v91, v179, v11
	v_cndmask_b32_e64 v14, 0, v3, s[40:41]
	v_add_f32_e32 v3, v91, v81
	v_mov_b32_e32 v153, v91
	v_mov_b32_e32 v11, v9
	v_add_f32_e32 v3, v90, v3
	v_add_f32_e32 v90, v152, v10
	v_add_f32_e32 v91, v153, v11
	v_add_f32_e32 v1, 0, v81
	v_add_f32_e32 v9, v91, v81
	ds_bpermute_b32 v173, v67, v190
	v_add_f32_e32 v1, v80, v1
	v_add_f32_e32 v9, v90, v9
	v_add_f32_e32 v12, v12, v13
	v_cndmask_b32_e64 v13, 0, v79, s[38:39]
	v_exp_f32_e32 v1, v1
	v_exp_f32_e32 v3, v3
	v_exp_f32_e32 v79, v9
	v_mov_b32_e32 v73, v91
	s_nop 0
	v_add_f32_e32 v8, v72, v8
	v_add_f32_e32 v9, v73, v10
	v_add_f32_e32 v175, v69, v75
	v_add_f32_e32 v9, v9, v81
	v_add_f32_e32 v147, 0, v7
	s_nop 0
	s_nop 0
	v_add_f32_e32 v80, v146, v6
	v_add_f32_e32 v81, v147, v5
	v_fmac_f32_e32 v4, 0x3e38aa3b, v68
	v_add_f32_e32 v68, v174, v176
	v_add_f32_e32 v69, v175, v177
	v_cndmask_b32_e64 v11, 0, v1, s[34:35]
	v_cndmask_b32_e64 v10, 0, v3, s[30:31]
	s_waitcnt lgkmcnt(0)
	v_cndmask_b32_e64 v1, 0, v173, s[8:9]
	v_add_f32_e32 v3, v6, v81
	v_add_f32_e32 v6, v141, v69
	s_nop 0
	v_add_f32_e32 v1, v1, v6
	v_fmac_f32_e32 v7, 0x3e38aa3b, v71
	v_add_f32_e32 v90, v168, v172
	v_add_f32_e32 v91, v190, v173
	v_add_f32_e32 v6, 0, v1
	v_fmac_f32_e32 v5, 0x3e38aa3b, v70
	v_add_f32_e32 v90, v90, v68
	v_add_f32_e32 v91, v91, v69
	v_add_f32_e32 v6, v7, v6
	v_add_f32_e32 v7, v147, v1
	ds_bpermute_b32 v67, v67, v90
	v_add_f32_e32 v5, v5, v7
	v_add_f32_e32 v7, v81, v1
	v_add_f32_e32 v7, v80, v7
	v_add_f32_e32 v1, v3, v1
	v_exp_f32_e32 v6, v6
	v_exp_f32_e32 v5, v5
	v_exp_f32_e32 v68, v7
	v_add_f32_e32 v1, v4, v1
	v_exp_f32_e32 v1, v1
	s_waitcnt lgkmcnt(0)
	v_cndmask_b32_e64 v177, 0, v67, s[8:9]
	v_add_f32_e32 v143, v141, v91
	v_cndmask_b32_e64 v7, 0, v6, s[24:25]
	v_cndmask_b32_e64 v6, 0, v5, s[22:23]
	v_cndmask_b32_e64 v5, 0, v68, s[18:19]
	v_add_f32_e32 v68, v142, v176
	v_add_f32_e32 v69, v143, v177
	v_cndmask_b32_e64 v4, 0, v1, s[16:17]
	v_add_f32_e32 v1, 0, v69
	v_mov_b32_e32 v171, v193
	v_mov_b32_e32 v175, v176
	v_add_f32_e32 v1, v68, v1
	v_add_f32_e32 v80, v170, v174
	v_add_f32_e32 v81, v171, v175
	v_exp_f32_e32 v68, v1
	v_add_f32_e32 v1, v81, v69
	s_nop 0
	v_mov_b32_e32 v173, v174
	v_add_f32_e32 v1, v80, v1
	v_add_f32_e32 v2, v2, v172
	v_add_f32_e32 v3, v81, v173
	v_exp_f32_e32 v71, v1
	v_add_f32_e32 v1, v3, v69
	v_add_f32_e32 v1, v2, v1
	v_exp_f32_e32 v73, v1
	s_nop 0
	v_mov_b32_e32 v169, v172
	v_add_f32_e32 v0, v0, v168
	v_add_f32_e32 v1, v3, v169
	v_add_f32_e32 v17, v200, v17
	v_add_f32_e32 v1, v1, v69
	v_add_f32_e32 v8, v8, v9
	v_add_f32_e32 v0, v0, v1
	v_exp_f32_e32 v30, v30
	v_exp_f32_e32 v17, v17
	v_exp_f32_e32 v12, v12
	v_exp_f32_e32 v8, v8
	v_exp_f32_e32 v0, v0
	v_add_f32_e32 v67, v90, v67
	s_movk_i32 s76, 0x1d00
	v_cndmask_b32_e64 v30, 0, v30, s[72:73]
	v_cndmask_b32_e64 v17, 0, v17, s[46:47]
	v_cndmask_b32_e64 v12, 0, v12, s[36:37]
	v_cndmask_b32_e64 v9, 0, v79, s[28:29]
	v_cndmask_b32_e64 v8, 0, v8, s[26:27]
	s_mov_b64 s[18:19], s[2:3]
	s_mov_b32 s2, s33
	s_movk_i32 s33, 0x600
	v_cndmask_b32_e64 v3, 0, v68, s[14:15]
	v_readlane_b32 s14, v254, 48
	v_readlane_b32 s3, v254, 51
	v_cndmask_b32_e64 v2, 0, v71, s[12:13]
	v_readlane_b32 s12, v254, 50
	v_cndmask_b32_e64 v1, 0, v73, s[0:1]
	v_cndmask_b32_e32 v0, 0, v0, vcc
	v_add_f32_e32 v67, v67, v91
	s_mov_b64 s[0:1], 0
.LBB0_503:
	s_andn2_b64 vcc, exec, s[0:1]
	s_cbranch_vccnz .LBB0_505
	v_exp_f32_e64 v0, -|v142|
	v_min_f32_e64 v1, -v142, 0
	v_and_b32_e32 v2, 64, v225
	v_add_u32_e32 v2, 64, v2
	v_add_f32_e32 v0, 1.0, v0
	v_log_f32_e32 v0, v0
	s_nop 0
	s_mov_b64 s[0:1], 0x3e38aa3b
	v_mul_f32_e32 v14, s0, v95
	v_mul_f32_e32 v15, s1, v141
	v_sub_f32_e32 v0, v1, v0
	v_exp_f32_e64 v1, -|v144|
	v_min_f32_e64 v22, -v192, 0
	v_min_f32_e64 v23, -v14, 0
	v_add_f32_e32 v24, s0, v95
	v_add_f32_e32 v25, s1, v141
	v_add_f32_e32 v1, 1.0, v1
	v_log_f32_e32 v3, v1
	v_exp_f32_e64 v1, -|v150|
	v_mov_b32_e32 v15, v25
	v_min_f32_e64 v18, -v164, 0
	v_min_f32_e64 v19, -v162, 0
	v_add_f32_e32 v1, 1.0, v1
	v_log_f32_e32 v7, v1
	v_exp_f32_e64 v1, -|v164|
	v_mov_b32_e32 v165, v193
	v_min_f32_e64 v20, -v166, 0
	v_mov_b32_e32 v140, v87
	v_add_f32_e32 v1, 1.0, v1
	v_log_f32_e32 v16, v1
	v_exp_f32_e64 v1, -|v166|
	v_min_f32_e64 v9, -v150, 0
	v_min_f32_e64 v8, -v152, 0
	v_min_f32_e64 v5, -v144, 0
	v_add_f32_e32 v1, 1.0, v1
	v_log_f32_e32 v12, v1
	v_exp_f32_e64 v1, -|v192|
	s_nop 0
	v_add_f32_e32 v1, 1.0, v1
	v_log_f32_e32 v10, v1
	v_xor_b32_e32 v1, 32, v225
	v_cmp_lt_i32_e32 vcc, v1, v2
	s_nop 1
	v_cndmask_b32_e32 v1, v225, v1, vcc
	v_lshlrev_b32_e32 v80, 2, v1
	v_exp_f32_e64 v1, -|v14|
	s_nop 0
	v_add_f32_e32 v1, 1.0, v1
	v_log_f32_e32 v11, v1
	s_nop 0
	v_add_f32_e64 v22, v22, -v10
	v_add_f32_e64 v23, v23, -v11
	s_nop 0
	v_add_f32_e32 v24, v192, v22
	v_add_f32_e32 v25, v193, v23
	v_pk_mov_b32 v[26:27], v[92:93], v[22:23] op_sel:[1,0]
	s_nop 0
	v_mul_f32_e32 v28, v26, v196
	v_mul_f32_e32 v29, v27, v25
	v_add_f32_e32 v10, v22, v22
	v_add_f32_e32 v11, v22, v23
	v_exp_f32_e64 v1, -|v28|
	v_min_f32_e64 v21, -v28, 0
	v_add_f32_e32 v26, v26, v24
	v_add_f32_e32 v27, v27, v25
	v_add_f32_e32 v1, 1.0, v1
	v_log_f32_e32 v13, v1
	v_exp_f32_e64 v1, -|v162|
	v_mov_b32_e32 v29, v27
	v_mov_b32_e32 v167, v27
	v_add_f32_e64 v20, v20, -v12
	v_add_f32_e64 v21, v21, -v13
	v_add_f32_e32 v1, 1.0, v1
	v_log_f32_e32 v17, v1
	v_add_f32_e32 v12, v20, v20
	v_add_f32_e32 v13, v20, v21
	v_add_f32_e32 v26, v166, v20
	v_add_f32_e32 v27, v167, v21
	v_add_f32_e64 v16, v18, -v16
	v_add_f32_e64 v17, v19, -v17
	s_nop 0
	v_add_f32_e32 v18, v164, v16
	v_add_f32_e32 v19, v165, v17
	v_pk_mov_b32 v[30:31], v[88:89], v[16:17] op_sel:[1,0]
	s_nop 0
	v_mul_f32_e32 v90, v30, v196
	v_mul_f32_e32 v91, v31, v19
	v_add_f32_e32 v30, v30, v196
	v_add_f32_e32 v31, v31, v19
	v_exp_f32_e64 v1, -|v90|
	v_min_f32_e64 v2, -v90, 0
	s_nop 0
	v_add_f32_e32 v68, v16, v17
	v_add_f32_e32 v69, v17, v16
	v_add_f32_e32 v1, 1.0, v1
	v_log_f32_e32 v1, v1
	v_mov_b32_e32 v91, v31
	v_sub_f32_e32 v10, v2, v1
	v_mov_b32_e32 v197, v10
	v_mul_f32_e32 v88, v196, v88
	v_mul_f32_e32 v89, v197, v31
	v_add_f32_e32 v30, v196, v30
	v_add_f32_e32 v31, v197, v31
	v_exp_f32_e64 v1, -|v88|
	v_min_f32_e64 v2, -v88, 0
	v_mov_b32_e32 v89, v31
	s_nop 0
	v_add_f32_e32 v1, 1.0, v1
	v_log_f32_e32 v1, v1
	s_nop 0
	v_sub_f32_e32 v12, v2, v1
	v_add_f32_e32 v92, v12, v10
	v_add_f32_e32 v93, v13, v11
	ds_bpermute_b32 v69, v80, v93
	s_waitcnt lgkmcnt(0)
	v_cndmask_b32_e64 v31, 0, v69, s[8:9]
	v_add_f32_e32 v14, v14, v23
	v_add_f32_e32 v15, v15, v31
	s_nop 0
	v_add_f32_e32 v1, v14, v15
	v_exp_f32_e32 v31, v1
	v_add_f32_e32 v1, v25, v15
	v_mov_b32_e32 v14, v21
	v_add_f32_e32 v1, v24, v1
	v_add_f32_e32 v20, v28, v14
	v_add_f32_e32 v21, v29, v15
	v_exp_f32_e32 v30, v1
	v_add_f32_e32 v1, v20, v21
	v_exp_f32_e32 v29, v1
	v_add_f32_e32 v1, v27, v15
	v_add_f32_e32 v14, v92, v68
	v_add_f32_e32 v15, v93, v69
	ds_bpermute_b32 v192, v80, v14
	v_mov_b32_e32 v20, v17
	v_add_f32_e32 v1, v26, v1
	v_exp_f32_e32 v28, v1
	s_waitcnt lgkmcnt(0)
	v_add_f32_e32 v14, v14, v192
	v_add_f32_e32 v15, v15, v193
	s_nop 0
	v_add_f32_e32 v163, v141, v15
	v_cndmask_b32_e64 v21, 0, v192, s[8:9]
	v_add_f32_e32 v16, v162, v20
	v_add_f32_e32 v17, v163, v21
	v_min_f32_e64 v20, -v84, 0
	v_add_f32_e32 v1, v16, v17
	v_exp_f32_e32 v27, v1
	v_add_f32_e32 v1, v19, v17
	s_nop 0
	v_add_f32_e32 v1, v18, v1
	v_add_f32_e32 v10, v90, v10
	v_add_f32_e32 v11, v91, v17
	s_nop 0
	v_exp_f32_e32 v26, v1
	v_add_f32_e32 v1, v10, v11
	v_add_f32_e32 v10, v88, v12
	v_add_f32_e32 v11, v89, v17
	v_exp_f32_e32 v25, v1
	v_add_f32_e32 v1, v10, v11
	v_add_f32_e32 v10, v14, v15
	v_add_f32_e32 v11, v15, v14
	v_exp_f32_e32 v24, v1
	s_nop 0
	v_mul_f32_e32 v12, v140, v196
	v_mul_f32_e32 v13, v141, v10
	v_add_f32_e32 v14, v140, v196
	v_add_f32_e32 v15, v141, v10
	v_exp_f32_e64 v1, -|v12|
	v_mov_b32_e32 v13, v15
	v_min_f32_e64 v17, -v12, 0
	v_min_f32_e64 v16, -v160, 0
	v_add_f32_e32 v1, 1.0, v1
	v_log_f32_e32 v15, v1
	v_exp_f32_e64 v1, -|v160|
	s_nop 0
	s_nop 0
	v_add_f32_e32 v1, 1.0, v1
	v_log_f32_e32 v14, v1
	s_nop 0
	v_add_f32_e64 v14, v16, -v14
	v_add_f32_e64 v15, v17, -v15
	s_nop 0
	v_mov_b32_e32 v87, v15
	v_mul_f32_e32 v16, s0, v86
	v_mul_f32_e32 v17, s1, v87
	v_add_f32_e32 v18, s0, v14
	v_add_f32_e32 v19, s1, v15
	v_exp_f32_e64 v1, -|v16|
	v_mov_b32_e32 v17, v19
	v_min_f32_e64 v21, -v16, 0
	v_min_f32_e64 v86, -v156, 0
	v_add_f32_e32 v1, 1.0, v1
	v_log_f32_e32 v19, v1
	v_exp_f32_e64 v1, -|v84|
	s_nop 0
	v_add_f32_e32 v1, 1.0, v1
	v_log_f32_e32 v18, v1
	s_nop 0
	v_add_f32_e64 v18, v20, -v18
	v_add_f32_e64 v19, v21, -v19
	s_nop 0
	v_add_f32_e32 v20, v18, v14
	v_add_f32_e32 v21, v19, v15
	s_nop 0
	v_add_f32_e32 v1, v20, v21
	ds_bpermute_b32 v2, v80, v1
	s_nop 0
	s_waitcnt lgkmcnt(0)
	v_add_f32_e32 v11, v1, v2
	v_exp_f32_e64 v1, -|v158|
	v_cndmask_b32_e64 v21, 0, v2, s[8:9]
	v_add_f32_e32 v12, v12, v15
	v_add_f32_e32 v13, v13, v21
	v_min_f32_e64 v2, -v154, 0
	v_add_f32_e32 v4, v12, v13
	s_nop 0
	v_add_f32_e32 v20, v16, v19
	v_add_f32_e32 v21, v17, v13
	v_add_f32_e32 v16, v18, v16
	v_add_f32_e32 v17, v19, v17
	v_add_f32_e32 v1, 1.0, v1
	v_mov_b32_e32 v12, v14
	v_add_f32_e32 v15, v14, v17
	v_add_f32_e32 v14, v14, v16
	v_log_f32_e32 v16, v1
	v_exp_f32_e64 v1, -|v156|
	v_mov_b32_e32 v161, v17
	v_mov_b32_e32 v85, v15
	v_mov_b32_e32 v19, v13
	v_add_f32_e32 v1, 1.0, v1
	v_exp_f32_e32 v23, v4
	v_add_f32_e32 v4, v20, v21
	v_add_f32_e32 v20, v160, v12
	v_add_f32_e32 v21, v161, v13
	v_add_f32_e32 v12, v84, v18
	v_add_f32_e32 v13, v85, v19
	v_log_f32_e32 v84, v1
	v_exp_f32_e64 v1, -|v154|
	v_exp_f32_e32 v22, v4
	v_add_f32_e32 v4, v20, v21
	v_exp_f32_e32 v21, v4
	v_add_f32_e32 v1, 1.0, v1
	v_log_f32_e32 v1, v1
	v_add_f32_e32 v4, v12, v13
	v_mov_b32_e32 v13, v10
	v_min_f32_e64 v18, -v158, 0
	v_sub_f32_e32 v12, v2, v1
	s_nop 0
	v_mul_f32_e32 v68, s0, v78
	v_mul_f32_e32 v69, s1, v12
	v_add_f32_e32 v78, s0, v78
	v_add_f32_e32 v79, s1, v12
	v_exp_f32_e64 v1, -|v68|
	v_min_f32_e64 v2, -v68, 0
	s_nop 0
	v_mov_b32_e32 v69, v79
	v_add_f32_e32 v1, 1.0, v1
	v_log_f32_e32 v1, v1
	v_exp_f32_e32 v20, v4
	v_exp_f32_e64 v4, -|v152|
	v_sub_f32_e32 v10, v2, v1
	v_add_f32_e32 v14, v10, v12
	v_add_f32_e32 v15, v11, v13
	v_add_f32_e32 v4, 1.0, v4
	s_nop 0
	v_mul_f32_e32 v88, v196, v83
	v_mul_f32_e32 v89, v141, v15
	v_add_f32_e32 v90, v196, v14
	v_add_f32_e32 v91, v141, v15
	v_exp_f32_e64 v1, -|v88|
	v_min_f32_e64 v19, -v88, 0
	v_mov_b32_e32 v89, v91
	s_nop 0
	v_add_f32_e32 v1, 1.0, v1
	v_log_f32_e32 v17, v1
	v_log_f32_e32 v6, v4
	v_add_f32_e64 v16, v18, -v16
	v_add_f32_e64 v17, v19, -v17
	s_nop 0
	s_nop 0
	v_mul_f32_e32 v82, s0, v82
	v_mul_f32_e32 v83, s1, v17
	v_add_f32_e32 v18, s0, v16
	v_add_f32_e32 v19, s1, v17
	v_exp_f32_e64 v1, -|v82|
	v_min_f32_e64 v87, -v82, 0
	v_mov_b32_e32 v83, v19
	v_add_f32_e64 v6, v8, -v6
	v_add_f32_e64 v7, v9, -v7
	v_add_f32_e32 v1, 1.0, v1
	v_log_f32_e32 v85, v1
	v_mov_b32_e32 v75, v7
	v_mul_f32_e32 v8, s0, v74
	v_mul_f32_e32 v9, s1, v75
	v_mov_b32_e32 v192, v7
	v_add_f32_e64 v84, v86, -v84
	v_add_f32_e64 v85, v87, -v85
	v_exp_f32_e64 v4, -|v8|
	v_add_f32_e32 v18, v84, v16
	v_add_f32_e32 v19, v85, v17
	v_add_f32_e32 v92, v84, v82
	v_add_f32_e32 v93, v85, v83
	v_add_f32_e32 v86, v18, v19
	v_add_f32_e32 v87, v19, v18
	ds_bpermute_b32 v91, v80, v86
	v_mov_b32_e32 v18, v17
	v_add_f32_e32 v94, v16, v92
	v_add_f32_e32 v95, v16, v93
	v_mov_b32_e32 v159, v93
	v_mov_b32_e32 v157, v95
	s_waitcnt lgkmcnt(0)
	v_cndmask_b32_e64 v19, 0, v91, s[8:9]
	v_add_f32_e32 v88, v88, v18
	v_add_f32_e32 v89, v89, v19
	v_add_f32_e32 v4, 1.0, v4
	v_add_f32_e32 v1, v88, v89
	v_mov_b32_e32 v88, v85
	v_add_f32_e32 v82, v82, v88
	v_add_f32_e32 v83, v83, v89
	s_nop 0
	v_exp_f32_e32 v19, v1
	v_add_f32_e32 v1, v82, v83
	v_add_f32_e32 v16, v158, v16
	v_add_f32_e32 v17, v159, v89
	s_nop 0
	v_exp_f32_e32 v18, v1
	v_add_f32_e32 v1, v16, v17
	v_add_f32_e32 v82, v156, v84
	v_add_f32_e32 v83, v157, v89
	v_exp_f32_e32 v17, v1
	v_add_f32_e32 v1, v82, v83
	v_mul_f32_e32 v82, v196, v77
	v_mul_f32_e32 v83, v10, v79
	v_exp_f32_e32 v16, v1
	v_exp_f32_e64 v1, -|v82|
	v_min_f32_e64 v2, -v82, 0
	v_add_f32_e32 v78, v196, v77
	v_add_f32_e32 v79, v10, v79
	v_add_f32_e32 v1, 1.0, v1
	v_log_f32_e32 v1, v1
	s_nop 0
	v_mov_b32_e32 v83, v79
	v_sub_f32_e32 v90, v2, v1
	s_nop 0
	v_mul_f32_e32 v76, v196, v76
	v_mul_f32_e32 v77, v90, v79
	v_add_f32_e32 v78, v196, v78
	v_add_f32_e32 v79, v90, v79
	v_exp_f32_e64 v1, -|v76|
	v_min_f32_e64 v2, -v76, 0
	v_mov_b32_e32 v77, v79
	v_mov_b32_e32 v79, v86
	v_add_f32_e32 v1, 1.0, v1
	v_log_f32_e32 v1, v1
	s_nop 0
	v_sub_f32_e32 v78, v2, v1
	v_add_f32_e32 v84, v78, v90
	v_add_f32_e32 v85, v79, v91
	s_nop 0
	v_add_f32_e32 v84, v84, v14
	v_add_f32_e32 v85, v85, v15
	ds_bpermute_b32 v1, v80, v84
	v_add_f32_e32 v155, v141, v85
	s_waitcnt lgkmcnt(0)
	v_cndmask_b32_e64 v13, 0, v1, s[8:9]
	v_add_f32_e32 v86, v12, v154
	v_add_f32_e32 v87, v13, v155
	v_add_f32_e32 v1, v84, v1
	s_nop 0
	v_add_f32_e32 v2, v86, v87
	v_add_f32_e32 v10, v68, v10
	v_add_f32_e32 v11, v69, v87
	v_mov_b32_e32 v91, v87
	v_exp_f32_e32 v15, v2
	v_add_f32_e32 v2, v10, v11
	v_add_f32_e32 v10, v82, v90
	v_add_f32_e32 v11, v83, v91
	s_nop 0
	v_exp_f32_e32 v14, v2
	v_add_f32_e32 v2, v10, v11
	v_add_f32_e32 v10, v76, v78
	v_add_f32_e32 v11, v77, v87
	v_exp_f32_e32 v13, v2
	v_add_f32_e32 v2, v10, v11
	v_add_f32_e32 v10, s0, v6
	v_add_f32_e32 v11, s1, v7
	v_min_f32_e64 v69, -v8, 0
	v_mov_b32_e32 v9, v11
	v_log_f32_e32 v11, v4
	v_exp_f32_e64 v4, -|v72|
	v_min_f32_e64 v68, -v72, 0
	v_add_f32_e32 v1, v1, v85
	v_exp_f32_e32 v12, v2
	v_add_f32_e32 v4, 1.0, v4
	v_log_f32_e32 v10, v4
	v_add_f32_e32 v2, v141, v1
	v_mov_b32_e32 v78, v0
	v_mov_b32_e32 v79, v193
	v_add_f32_e64 v68, v68, -v10
	v_add_f32_e64 v69, v69, -v11
	s_nop 0
	v_add_f32_e32 v10, v68, v6
	v_add_f32_e32 v11, v69, v7
	s_nop 0
	v_add_f32_e32 v4, v10, v11
	ds_bpermute_b32 v67, v80, v4
	s_waitcnt lgkmcnt(0)
	v_cndmask_b32_e64 v7, 0, v67, s[8:9]
	v_add_f32_e32 v151, v7, v2
	v_add_f32_e32 v10, v150, v192
	v_add_f32_e32 v11, v151, v193
	v_mov_b32_e32 v150, v69
	v_add_f32_e32 v2, v10, v11
	v_add_f32_e32 v74, v8, v150
	v_add_f32_e32 v75, v9, v151
	v_exp_f32_e32 v11, v2
	v_add_f32_e32 v2, v74, v75
	v_add_f32_e32 v74, v68, v8
	v_add_f32_e32 v75, v69, v9
	s_nop 0
	v_mov_b32_e32 v153, v75
	v_add_f32_e32 v8, v152, v6
	v_add_f32_e32 v9, v153, v151
	s_nop 0
	v_mov_b32_e32 v69, v6
	v_exp_f32_e32 v10, v2
	v_add_f32_e32 v2, v8, v9
	v_add_f32_e32 v6, v72, v68
	v_add_f32_e32 v7, v75, v69
	v_exp_f32_e32 v9, v2
	v_add_f32_e32 v2, v7, v151
	v_add_f32_e32 v2, v6, v2
	v_exp_f32_e32 v8, v2
	v_exp_f32_e64 v2, -|v146|
	v_add_f32_e32 v69, v4, v67
	v_min_f32_e64 v4, -v146, 0
	s_nop 0
	v_add_f32_e32 v2, 1.0, v2
	v_log_f32_e32 v2, v2
	v_mul_f32_e32 v82, s0, v66
	v_mul_f32_e32 v83, s1, v0
	v_add_f32_e32 v66, s0, v66
	v_add_f32_e32 v67, s1, v0
	v_add_f32_e64 v2, v4, -v2
	v_add_f32_e64 v3, v5, -v3
	s_nop 0
	s_nop 0
	v_mul_f32_e32 v4, s0, v70
	v_mul_f32_e32 v5, s1, v3
	v_add_f32_e32 v6, s0, v2
	v_add_f32_e32 v7, s1, v3
	v_min_f32_e64 v71, -v4, 0
	v_exp_f32_e64 v6, -|v4|
	v_mov_b32_e32 v5, v7
	v_min_f32_e64 v70, -v148, 0
	v_mov_b32_e32 v192, v3
	v_add_f32_e32 v6, 1.0, v6
	v_log_f32_e32 v7, v6
	v_exp_f32_e64 v6, -|v148|
	v_mov_b32_e32 v66, v65
	s_nop 0
	v_mov_b32_e32 v83, v67
	v_add_f32_e32 v6, 1.0, v6
	v_log_f32_e32 v6, v6
	s_nop 0
	v_add_f32_e64 v72, v70, -v6
	v_add_f32_e64 v73, v71, -v7
	s_nop 0
	v_add_f32_e32 v6, v72, v2
	v_add_f32_e32 v7, v73, v3
	s_nop 0
	v_add_f32_e32 v74, v6, v7
	v_add_f32_e32 v75, v7, v6
	v_add_f32_e32 v6, v72, v4
	v_add_f32_e32 v7, v73, v5
	ds_bpermute_b32 v71, v80, v74
	v_exp_f32_e64 v6, -|v82|
	v_mov_b32_e32 v149, v7
	v_mov_b32_e32 v147, v7
	v_min_f32_e64 v7, -v82, 0
	v_add_f32_e32 v6, 1.0, v6
	v_log_f32_e32 v6, v6
	s_waitcnt lgkmcnt(0)
	v_cndmask_b32_e64 v3, 0, v71, s[8:9]
	v_add_f32_e32 v76, v148, v72
	v_add_f32_e32 v77, v149, v2
	v_sub_f32_e32 v68, v7, v6
	v_add_f32_e32 v0, v68, v0
	v_add_f32_e32 v1, v69, v1
	s_nop 0
	v_add_f32_e32 v6, v141, v1
	v_add_f32_e32 v145, v3, v6
	v_add_f32_e32 v6, v144, v192
	v_add_f32_e32 v7, v145, v193
	v_mov_b32_e32 v144, v73
	v_mul_f32_e32 v72, v196, v66
	v_mul_f32_e32 v73, v68, v67
	v_add_f32_e32 v3, v6, v7
	v_exp_f32_e64 v65, -|v72|
	v_add_f32_e32 v4, v4, v144
	v_add_f32_e32 v5, v5, v145
	v_exp_f32_e32 v7, v3
	v_add_f32_e32 v3, v4, v5
	v_exp_f32_e32 v6, v3
	s_nop 0
	v_add_f32_e32 v2, v146, v2
	v_add_f32_e32 v3, v147, v145
	v_add_f32_e32 v65, 1.0, v65
	v_add_f32_e32 v2, v2, v3
	v_log_f32_e32 v65, v65
	v_exp_f32_e32 v5, v2
	v_add_f32_e32 v2, v77, v145
	v_add_f32_e32 v2, v76, v2
	v_exp_f32_e32 v4, v2
	v_add_f32_e32 v2, v196, v66
	v_add_f32_e32 v3, v68, v67
	v_min_f32_e64 v66, -v72, 0
	v_sub_f32_e32 v70, v66, v65
	v_mov_b32_e32 v197, v70
	s_nop 0
	v_mov_b32_e32 v73, v3
	v_mul_f32_e32 v64, v196, v64
	v_mul_f32_e32 v65, v197, v3
	v_add_f32_e32 v2, v196, v2
	v_add_f32_e32 v3, v197, v3
	v_mov_b32_e32 v67, v74
	v_exp_f32_e64 v2, -|v64|
	v_mov_b32_e32 v65, v3
	v_min_f32_e64 v3, -v64, 0
	v_add_f32_e32 v2, 1.0, v2
	v_log_f32_e32 v2, v2
	s_nop 0
	v_sub_f32_e32 v66, v3, v2
	v_add_f32_e32 v2, v66, v70
	v_add_f32_e32 v3, v67, v71
	s_nop 0
	v_add_f32_e32 v74, v2, v0
	v_add_f32_e32 v75, v3, v1
	ds_bpermute_b32 v76, v80, v74
	v_add_f32_e32 v1, v141, v75
	s_waitcnt lgkmcnt(0)
	v_cndmask_b32_e64 v0, 0, v76, s[8:9]
	v_add_f32_e32 v143, v0, v1
	v_add_f32_e32 v0, v142, v78
	v_add_f32_e32 v1, v143, v79
	v_mov_b32_e32 v69, v143
	v_add_f32_e32 v0, v0, v1
	v_exp_f32_e32 v3, v0
	v_add_f32_e32 v0, v82, v68
	v_add_f32_e32 v1, v83, v69
	v_mov_b32_e32 v71, v143
	v_add_f32_e32 v0, v0, v1
	v_exp_f32_e32 v2, v0
	v_add_f32_e32 v0, v72, v70
	v_add_f32_e32 v1, v73, v71
	s_nop 0
	v_add_f32_e32 v0, v0, v1
	v_add_f32_e32 v64, v64, v66
	v_add_f32_e32 v65, v65, v143
	v_exp_f32_e32 v1, v0
	v_add_f32_e32 v0, v64, v65
	v_exp_f32_e32 v0, v0
	v_add_f32_e32 v64, v74, v76
	v_add_f32_e32 v67, v64, v75
